# de-phase sleep 24 instead of 10
# baseline (speedup 1.0000x reference)
.LBB0_242:
	s_andn2_b64 vcc, exec, s[48:49]
	s_cbranch_vccnz .LBB0_236
	s_lshl_b32 s48, s6, 8
	s_lshl_b32 s46, s80, 7
	s_ashr_i32 s49, s48, 31
	s_ashr_i32 s47, s46, 31
	s_lshl_b64 s[10:11], s[48:49], 11
	s_lshl_b64 s[50:51], s[46:47], 11
	s_add_u32 s10, s94, s10
	v_readfirstlane_b32 s5, v147
	v_add_u32_e32 v2, 0x400, v147
	s_addc_u32 s11, s95, s11
	v_mov_b32_e32 v0, v135
	s_mov_b32 m0, s5
	v_readfirstlane_b32 s5, v2
	v_add_u32_e32 v2, 0x800, v147
	v_mov_b32_e32 v130, v142
	global_load_lds_dwordx4 v0, s[10:11]
	s_mov_b32 m0, s5
	v_readfirstlane_b32 s5, v2
	v_add_u32_e32 v2, 0xc00, v147
	v_mov_b32_e32 v132, v143
	global_load_lds_dwordx4 v130, s[10:11]
	s_mov_b32 m0, s5
	v_readfirstlane_b32 s5, v2
	v_add_u32_e32 v2, 0x4000, v148
	s_add_u32 s52, s54, s50
	v_mov_b32_e32 v136, v144
	global_load_lds_dwordx4 v132, s[10:11]
	s_mov_b32 m0, s5
	v_readfirstlane_b32 s5, v2
	v_add_u32_e32 v2, 0x4400, v148
	s_addc_u32 s53, s55, s51
	v_mov_b32_e32 v138, v145
	global_load_lds_dwordx4 v136, s[10:11]
	s_mov_b32 m0, s5
	v_readfirstlane_b32 s5, v2
	v_mov_b32_e32 v140, v146
	global_load_lds_dwordx4 v138, s[52:53]
	s_mov_b32 m0, s5
	v_add_u32_e32 v4, 0x6000, v147
	v_mov_b32_e32 v131, v1
	global_load_lds_dwordx4 v140, s[52:53]
	v_readfirstlane_b32 s5, v4
	v_lshl_add_u64 v[2:3], s[10:11], 0, v[0:1]
	v_lshl_add_u64 v[2:3], v[2:3], 0, s[60:61]
	s_mov_b32 m0, s5
	v_add_u32_e32 v4, 0x6400, v147
	global_load_lds_dwordx4 v[2:3], off
	v_readfirstlane_b32 s5, v4
	v_lshl_add_u64 v[2:3], s[10:11], 0, v[130:131]
	v_lshl_add_u64 v[2:3], v[2:3], 0, s[60:61]
	s_mov_b32 m0, s5
	v_mov_b32_e32 v133, v1
	v_add_u32_e32 v4, 0x6800, v147
	global_load_lds_dwordx4 v[2:3], off
	v_readfirstlane_b32 s5, v4
	v_lshl_add_u64 v[2:3], s[10:11], 0, v[132:133]
	v_lshl_add_u64 v[2:3], v[2:3], 0, s[60:61]
	s_mov_b32 m0, s5
	v_mov_b32_e32 v137, v1
	v_add_u32_e32 v4, 0x6c00, v147
	global_load_lds_dwordx4 v[2:3], off
	v_readfirstlane_b32 s5, v4
	v_lshl_add_u64 v[2:3], s[10:11], 0, v[136:137]
	v_lshl_add_u64 v[2:3], v[2:3], 0, s[60:61]
	s_mov_b32 m0, s5
	v_mov_b32_e32 v139, v1
	v_add_u32_e32 v4, 0xa000, v148
	global_load_lds_dwordx4 v[2:3], off
	v_readfirstlane_b32 s5, v4
	v_lshl_add_u64 v[2:3], s[52:53], 0, v[138:139]
	v_lshl_add_u64 v[2:3], v[2:3], 0, s[86:87]
	s_mov_b32 m0, s5
	v_mov_b32_e32 v141, v1
	v_add_u32_e32 v4, 0xa400, v148
	global_load_lds_dwordx4 v[2:3], off
	v_readfirstlane_b32 s5, v4
	v_lshl_add_u64 v[2:3], s[52:53], 0, v[140:141]
	v_lshl_add_u64 v[2:3], v[2:3], 0, s[86:87]
	s_mov_b32 m0, s5
	s_andn2_b64 vcc, exec, s[28:29]
	global_load_lds_dwordx4 v[2:3], off
	s_cbranch_vccnz .LBB0_245
	s_sleep 24
